# P2 K-loop: hoisted LDS read bases, DMA issued between ds_reads instead of s_nop, saddr-form LDS-DMA
# speedup vs baseline: 1.0236x; 1.0166x over previous
; __device__ __forceinline__ int fresh_tid() { int t = threadIdx.x; asm volatile("" : "+v"(t)); return t; }
; #define PG8_STAGE(bufoff, gbase) PG8_STAGE_(bufoff, gbase, voffA)
; #define PG8_LDA(dst, b, h) do { _Pragma("unroll") for (int m = 0; m < 4; ++m) _Pragma("unroll") for (int k = 0; k < 2; ++k) dst[m][k] = *(const LAS bf16x8*)(lds + PG8_SA(b, h) + aoff + m * 2048 + k * 1024); } while (0)
; #define PG8_LDB(dst, b, h) do { _Pragma("unroll") for (int n = 0; n < 2; ++n) _Pragma("unroll") for (int k = 0; k < 2; ++k) dst[n][k] = *(const LAS bf16x8*)(lds + PG8_SB(b, h) + boff + n * 2048 + k * 1024); } while (0)
; #define PG8_MMA(ai, bj, At, Bt) do { __builtin_amdgcn_s_setprio(1); _Pragma("unroll") for (int m = 0; m < 4; ++m) _Pragma("unroll") for (int n = 0; n < 2; ++n) _Pragma("unroll") for (int k = 0; k < 2; ++k) \
;         acc[ai][bj][m][n] = __builtin_amdgcn_mfma_f32_16x16x32_bf16(Bt[n][k], At[m][k], acc[ai][bj][m][n], 0, 0, 0); __builtin_amdgcn_s_setprio(0); } while (0)
; #define PG8_WAIT_L(n) asm volatile("s_waitcnt lgkmcnt(" #n ")" ::: "memory")
; #define PG8_BAR __builtin_amdgcn_s_barrier()
; #define PG8_SCHED __builtin_amdgcn_sched_barrier(0)
; template <class Epi>
; __device__ __forceinline__ void gemm_phase(LAS unsigned char* lds, const Gemm g, const StaticOrder& S, const Epi& E) {
;     ...
;     for (;;) {
;         const bool has_next = S.next(ui + 1, nxt);
;         const char* nA = has_next ? (const char*)g.A + (size_t)nxt.pm * tstep : cA; const char* nB = has_next ? (const char*)g.Bt + (size_t)nxt.pn * tstep : cB;
;         for (int t = 0; t < nt; t += 2) {
;             const bool last = (t == nt - 2);
;             const char* a1 = cA + (size_t)(t + 1) * kstep;
;             const char* a2 = last ? nA : cA + (size_t)(t + 2) * kstep; const char* b2 = last ? nB : cB + (size_t)(t + 2) * kstep;
;             const char* a3 = a2 + kstep; const char* b3 = b2 + kstep;
;             if constexpr (Epi::RESCALE) { if (t != 0 && (t & 7) == 0) { const int t2 = fresh_tid(); const int w2 = __builtin_amdgcn_readfirstlane(t2 >> 6); E.rescale(acc, cur, t >> 3, w2 >> 2, w2 & 3, t2 & 15, (t2 >> 4) & 3); } }
;             PG8_LDB(B0, 0, 0); PG8_SCHED; PG8_LDA(At, 0, 0); PG8_STAGE(PG8_SA(1, 1), a1 + hstep);
;             PG8_WAIT_L(8); PG8_BAR; PG8_WAIT_L(0); PG8_MMA(0, 0, At, B0); PG8_BAR; PG8_SCHED;
.LBB0_425:
	v_mov_b64_e32 v[2:3], 0x8a0
	s_ashr_i32 s35, s34, 31
	v_cmp_lt_i64_e32 vcc, s[44:45], v[2:3]
	s_lshl_b64 s[44:45], s[34:35], 20
	s_add_u32 s46, s51, s44
	s_addc_u32 s47, s52, s45
	s_and_b64 s[44:45], vcc, exec
	s_cselect_b32 s35, s47, s31
	s_cselect_b32 s84, s46, s30
	s_ashr_i32 s25, s24, 31
	s_lshl_b64 s[44:45], s[24:25], 20
	s_add_u32 s48, s53, s44
	s_addc_u32 s49, s54, s45
	s_and_b64 s[44:45], vcc, exec
	s_cselect_b32 s25, s49, s21
	s_cselect_b32 s85, s48, s20
	s_add_u32 s30, s30, 0x80080
	s_addc_u32 s31, s31, 0
	s_add_u32 s86, s20, 0x100
	v_mov_b32_e32 v2, 0
	s_addc_u32 s87, s21, 0
	s_mov_b32 s88, -2
	v_mov_b32_e32 v3, v2
	v_mov_b32_e32 v4, v2
	v_mov_b32_e32 v5, v2
	v_mov_b32_e32 v6, v2
	v_mov_b32_e32 v7, v2
	v_mov_b32_e32 v8, v2
	v_mov_b32_e32 v9, v2
	v_mov_b32_e32 v22, v2
	v_mov_b32_e32 v23, v2
	v_mov_b32_e32 v24, v2
	v_mov_b32_e32 v25, v2
	v_mov_b32_e32 v18, v2
	v_mov_b32_e32 v19, v2
	v_mov_b32_e32 v20, v2
	v_mov_b32_e32 v21, v2
	v_mov_b32_e32 v38, v2
	v_mov_b32_e32 v39, v2
	v_mov_b32_e32 v40, v2
	v_mov_b32_e32 v41, v2
	v_mov_b32_e32 v34, v2
	v_mov_b32_e32 v35, v2
	v_mov_b32_e32 v36, v2
	v_mov_b32_e32 v37, v2
	s_waitcnt vmcnt(0)
	v_mov_b32_e32 v54, v2
	v_mov_b32_e32 v55, v2
	v_mov_b32_e32 v56, v2
	v_mov_b32_e32 v57, v2
	v_mov_b32_e32 v50, v2
	v_mov_b32_e32 v51, v2
	v_mov_b32_e32 v52, v2
	v_mov_b32_e32 v53, v2
	v_mov_b32_e32 v14, v2
	v_mov_b32_e32 v15, v2
	v_mov_b32_e32 v16, v2
	v_mov_b32_e32 v17, v2
	v_mov_b32_e32 v10, v2
	v_mov_b32_e32 v11, v2
	v_mov_b32_e32 v12, v2
	v_mov_b32_e32 v13, v2
	v_mov_b32_e32 v30, v2
	v_mov_b32_e32 v31, v2
	v_mov_b32_e32 v32, v2
	v_mov_b32_e32 v33, v2
	v_mov_b32_e32 v26, v2
	v_mov_b32_e32 v27, v2
	v_mov_b32_e32 v28, v2
	v_mov_b32_e32 v29, v2
	v_mov_b32_e32 v46, v2
	v_mov_b32_e32 v47, v2
	v_mov_b32_e32 v48, v2
	v_mov_b32_e32 v49, v2
	v_mov_b32_e32 v42, v2
	v_mov_b32_e32 v43, v2
	v_mov_b32_e32 v44, v2
	v_mov_b32_e32 v45, v2
	v_mov_b32_e32 v62, v2
	v_mov_b32_e32 v63, v2
	v_mov_b32_e32 v64, v2
	v_mov_b32_e32 v65, v2
	v_mov_b32_e32 v58, v2
	v_mov_b32_e32 v59, v2
	v_mov_b32_e32 v60, v2
	v_mov_b32_e32 v61, v2
	v_mov_b32_e32 v70, v2
	v_mov_b32_e32 v71, v2
	v_mov_b32_e32 v72, v2
	v_mov_b32_e32 v73, v2
	v_mov_b32_e32 v66, v2
	v_mov_b32_e32 v67, v2
	v_mov_b32_e32 v68, v2
	v_mov_b32_e32 v69, v2
	v_mov_b32_e32 v102, v2
	v_mov_b32_e32 v103, v2
	v_mov_b32_e32 v104, v2
	v_mov_b32_e32 v105, v2
	v_mov_b32_e32 v98, v2
	v_mov_b32_e32 v99, v2
	v_mov_b32_e32 v100, v2
	v_mov_b32_e32 v101, v2
	v_mov_b32_e32 v118, v2
	v_mov_b32_e32 v119, v2
	v_mov_b32_e32 v120, v2
	v_mov_b32_e32 v121, v2
	v_mov_b32_e32 v114, v2
	v_mov_b32_e32 v115, v2
	v_mov_b32_e32 v116, v2
	v_mov_b32_e32 v117, v2
	v_mov_b32_e32 v134, v2
	v_mov_b32_e32 v135, v2
	v_mov_b32_e32 v136, v2
	v_mov_b32_e32 v137, v2
	v_mov_b32_e32 v130, v2
	v_mov_b32_e32 v131, v2
	v_mov_b32_e32 v132, v2
	v_mov_b32_e32 v133, v2
	v_mov_b32_e32 v82, v2
	v_mov_b32_e32 v83, v2
	v_mov_b32_e32 v84, v2
	v_mov_b32_e32 v85, v2
	v_mov_b32_e32 v78, v2
	v_mov_b32_e32 v79, v2
	v_mov_b32_e32 v80, v2
	v_mov_b32_e32 v81, v2
	v_mov_b32_e32 v110, v2
	v_mov_b32_e32 v111, v2
	v_mov_b32_e32 v112, v2
	v_mov_b32_e32 v113, v2
	v_mov_b32_e32 v106, v2
	v_mov_b32_e32 v107, v2
	v_mov_b32_e32 v108, v2
	v_mov_b32_e32 v109, v2
	v_mov_b32_e32 v126, v2
	v_mov_b32_e32 v127, v2
	v_mov_b32_e32 v128, v2
	v_mov_b32_e32 v129, v2
	v_mov_b32_e32 v122, v2
	v_mov_b32_e32 v123, v2
	v_mov_b32_e32 v124, v2
	v_mov_b32_e32 v125, v2
	v_mov_b32_e32 v142, v2
	v_mov_b32_e32 v143, v2
	v_mov_b32_e32 v144, v2
	v_mov_b32_e32 v145, v2
	v_mov_b32_e32 v138, v2
	v_mov_b32_e32 v139, v2
	v_mov_b32_e32 v140, v2
	v_mov_b32_e32 v141, v2
	v_add_u32_e32 v148, 0x10000, v170
	v_add_u32_e32 v149, 0x14000, v170
	v_add_u32_e32 v150, 0x18000, v170
	v_add_u32_e32 v151, 0x1c000, v170
.LBB0_426:
	s_add_u32 s20, s30, 0xfff80080
	s_addc_u32 s21, s31, -1
	s_add_i32 s58, 0, 0x10000
	ds_read_b128 v[74:77], v148
	ds_read_b128 v[86:89], v148 offset:1024
	ds_read_b128 v[90:93], v148 offset:2048
	ds_read_b128 v[94:97], v148 offset:3072
	s_cmp_eq_u32 s88, 28
	s_cselect_b32 s45, s35, s21
	s_cselect_b32 s44, s84, s20
	s_cselect_b32 s21, s25, s87
	s_cselect_b32 s20, s85, s86
	s_add_u32 s100, s44, s16
	s_addc_u32 s101, s45, s17
	s_add_i32 m0, s62, 0xc000
	ds_read_b128 v[166:169], v171
	ds_read_b128 v[172:175], v171 offset:1024
	ds_read_b128 v[176:179], v171 offset:2048
	ds_read_b128 v[206:209], v171 offset:3072
	ds_read_b128 v[210:213], v171 offset:4096
	ds_read_b128 v[214:217], v171 offset:5120
	ds_read_b128 v[218:221], v171 offset:6144
	global_load_lds_dwordx4 v162, s[30:31]
	s_add_i32 m0, s62, 0xe000
	ds_read_b128 v[222:225], v171 offset:7168
	global_load_lds_dwordx4 v164, s[30:31]
	s_waitcnt lgkmcnt(8)
	s_barrier
	s_waitcnt lgkmcnt(0)
	s_setprio 1
	s_waitcnt lgkmcnt(0)
	v_mfma_f32_16x16x32_bf16 v[138:141], v[74:77], v[166:169], v[138:141]
	v_mfma_f32_16x16x32_bf16 v[142:145], v[90:93], v[166:169], v[142:145]
	v_mfma_f32_16x16x32_bf16 v[122:125], v[74:77], v[176:179], v[122:125]
	v_mfma_f32_16x16x32_bf16 v[126:129], v[90:93], v[176:179], v[126:129]
	v_mfma_f32_16x16x32_bf16 v[106:109], v[74:77], v[210:213], v[106:109]
	v_mfma_f32_16x16x32_bf16 v[110:113], v[90:93], v[210:213], v[110:113]
	v_mfma_f32_16x16x32_bf16 v[78:81], v[74:77], v[218:221], v[78:81]
	v_mfma_f32_16x16x32_bf16 v[82:85], v[90:93], v[218:221], v[82:85]
	v_mfma_f32_16x16x32_bf16 v[138:141], v[86:89], v[172:175], v[138:141]
	v_mfma_f32_16x16x32_bf16 v[142:145], v[94:97], v[172:175], v[142:145]
	v_mfma_f32_16x16x32_bf16 v[122:125], v[86:89], v[206:209], v[122:125]
	v_mfma_f32_16x16x32_bf16 v[126:129], v[94:97], v[206:209], v[126:129]
	v_mfma_f32_16x16x32_bf16 v[106:109], v[86:89], v[214:217], v[106:109]
	v_mfma_f32_16x16x32_bf16 v[110:113], v[94:97], v[214:217], v[110:113]
	v_mfma_f32_16x16x32_bf16 v[78:81], v[86:89], v[222:225], v[78:81]
	v_mfma_f32_16x16x32_bf16 v[82:85], v[94:97], v[222:225], v[82:85]
	s_setprio 0
	s_barrier
; #define PG8_STAGE(bufoff, gbase) PG8_STAGE_(bufoff, gbase, voffA)
; #define PG8_STAGEB(bufoff, gbase) PG8_STAGE_(bufoff, gbase, voffB)
; #define PG8_LDA(dst, b, h) do { _Pragma("unroll") for (int m = 0; m < 4; ++m) _Pragma("unroll") for (int k = 0; k < 2; ++k) dst[m][k] = *(const LAS bf16x8*)(lds + PG8_SA(b, h) + aoff + m * 2048 + k * 1024); } while (0)
; #define PG8_LDB(dst, b, h) do { _Pragma("unroll") for (int n = 0; n < 2; ++n) _Pragma("unroll") for (int k = 0; k < 2; ++k) dst[n][k] = *(const LAS bf16x8*)(lds + PG8_SB(b, h) + boff + n * 2048 + k * 1024); } while (0)
; #define PG8_MMA(ai, bj, At, Bt) do { __builtin_amdgcn_s_setprio(1); _Pragma("unroll") for (int m = 0; m < 4; ++m) _Pragma("unroll") for (int n = 0; n < 2; ++n) _Pragma("unroll") for (int k = 0; k < 2; ++k) \
;         acc[ai][bj][m][n] = __builtin_amdgcn_mfma_f32_16x16x32_bf16(Bt[n][k], At[m][k], acc[ai][bj][m][n], 0, 0, 0); __builtin_amdgcn_s_setprio(0); } while (0)
; #define PG8_WAIT_V(n) asm volatile("s_waitcnt vmcnt(" #n ")" ::: "memory")
; #define PG8_WAIT_L(n) asm volatile("s_waitcnt lgkmcnt(" #n ")" ::: "memory")
; #define PG8_BAR __builtin_amdgcn_s_barrier()
; #define PG8_SCHED __builtin_amdgcn_sched_barrier(0)
; template <class Epi>
; __device__ __forceinline__ void gemm_phase(LAS unsigned char* lds, const Gemm g, const StaticOrder& S, const Epi& E) {
;     ...
;             PG8_LDB(B1, 0, 1); PG8_STAGEB(PG8_SB(0, 0), b2);
;             PG8_BAR; PG8_WAIT_L(0); PG8_MMA(0, 1, At, B1); PG8_BAR;
;             PG8_LDA(At, 0, 1); PG8_STAGE(PG8_SA(0, 0), a2);
;             PG8_BAR; PG8_WAIT_L(0); PG8_MMA(1, 0, At, B0); PG8_BAR; PG8_SCHED;
;             PG8_STAGEB(PG8_SB(0, 1), b2 + hstep);
;             PG8_WAIT_V(6); PG8_BAR; PG8_MMA(1, 1, At, B1); PG8_BAR;
;             PG8_LDB(B0, 1, 0); PG8_SCHED; PG8_LDA(At, 1, 0); PG8_STAGE(PG8_SA(0, 1), a2 + hstep);
;             PG8_WAIT_L(8); PG8_BAR; PG8_WAIT_L(0); PG8_MMA(0, 0, At, B0); PG8_BAR; PG8_SCHED;
;             PG8_LDB(B1, 1, 1); PG8_STAGEB(PG8_SB(1, 0), b3);
	s_add_i32 s59, 0, 0x14000
	s_add_i32 s58, s58, s55
	s_mov_b32 m0, s58
	ds_read_b128 v[226:229], v149
	ds_read_b128 v[230:233], v149 offset:1024
	ds_read_b128 v[234:237], v149 offset:2048
	global_load_lds_dwordx4 v0, s[20:21]
	s_add_i32 m0, s58, 0x2000
	ds_read_b128 v[238:241], v149 offset:3072
	global_load_lds_dwordx4 v156, s[20:21]
	s_barrier
	s_waitcnt lgkmcnt(0)
	s_setprio 1
	s_waitcnt lgkmcnt(0)
	v_mfma_f32_16x16x32_bf16 v[130:133], v[226:229], v[166:169], v[130:133]
	v_mfma_f32_16x16x32_bf16 v[134:137], v[234:237], v[166:169], v[134:137]
	v_mfma_f32_16x16x32_bf16 v[114:117], v[226:229], v[176:179], v[114:117]
	v_mfma_f32_16x16x32_bf16 v[118:121], v[234:237], v[176:179], v[118:121]
	v_mfma_f32_16x16x32_bf16 v[98:101], v[226:229], v[210:213], v[98:101]
	v_mfma_f32_16x16x32_bf16 v[102:105], v[234:237], v[210:213], v[102:105]
	v_mfma_f32_16x16x32_bf16 v[66:69], v[226:229], v[218:221], v[66:69]
	v_mfma_f32_16x16x32_bf16 v[70:73], v[234:237], v[218:221], v[70:73]
	v_mfma_f32_16x16x32_bf16 v[130:133], v[230:233], v[172:175], v[130:133]
	v_mfma_f32_16x16x32_bf16 v[134:137], v[238:241], v[172:175], v[134:137]
	v_mfma_f32_16x16x32_bf16 v[114:117], v[230:233], v[206:209], v[114:117]
	v_mfma_f32_16x16x32_bf16 v[118:121], v[238:241], v[206:209], v[118:121]
	v_mfma_f32_16x16x32_bf16 v[98:101], v[230:233], v[214:217], v[98:101]
	v_mfma_f32_16x16x32_bf16 v[102:105], v[238:241], v[214:217], v[102:105]
	v_mfma_f32_16x16x32_bf16 v[66:69], v[230:233], v[222:225], v[66:69]
	v_mfma_f32_16x16x32_bf16 v[70:73], v[238:241], v[222:225], v[70:73]
	s_setprio 0
	s_mov_b32 m0, s62
	s_barrier
	ds_read_b128 v[166:169], v171 offset:16384
	ds_read_b128 v[172:175], v171 offset:17408
	ds_read_b128 v[176:179], v171 offset:18432
	ds_read_b128 v[206:209], v171 offset:19456
	ds_read_b128 v[210:213], v171 offset:20480
	ds_read_b128 v[214:217], v171 offset:21504
	ds_read_b128 v[218:221], v171 offset:22528
	global_load_lds_dwordx4 v160, s[44:45]
	s_mov_b32 m0, s63
	ds_read_b128 v[222:225], v171 offset:23552
	global_load_lds_dwordx4 v158, s[44:45]
	s_barrier
	s_waitcnt lgkmcnt(0)
	s_setprio 1
	s_waitcnt lgkmcnt(0)
	v_mfma_f32_16x16x32_bf16 v[58:61], v[74:77], v[166:169], v[58:61]
	v_mfma_f32_16x16x32_bf16 v[62:65], v[90:93], v[166:169], v[62:65]
	v_mfma_f32_16x16x32_bf16 v[42:45], v[74:77], v[176:179], v[42:45]
	v_mfma_f32_16x16x32_bf16 v[46:49], v[90:93], v[176:179], v[46:49]
	v_mfma_f32_16x16x32_bf16 v[26:29], v[74:77], v[210:213], v[26:29]
	v_mfma_f32_16x16x32_bf16 v[30:33], v[90:93], v[210:213], v[30:33]
	v_mfma_f32_16x16x32_bf16 v[10:13], v[74:77], v[218:221], v[10:13]
	v_mfma_f32_16x16x32_bf16 v[14:17], v[90:93], v[218:221], v[14:17]
	v_mfma_f32_16x16x32_bf16 v[58:61], v[86:89], v[172:175], v[58:61]
	v_mfma_f32_16x16x32_bf16 v[62:65], v[94:97], v[172:175], v[62:65]
	v_mfma_f32_16x16x32_bf16 v[42:45], v[86:89], v[206:209], v[42:45]
	v_mfma_f32_16x16x32_bf16 v[46:49], v[94:97], v[206:209], v[46:49]
	v_mfma_f32_16x16x32_bf16 v[26:29], v[86:89], v[214:217], v[26:29]
	v_mfma_f32_16x16x32_bf16 v[30:33], v[94:97], v[214:217], v[30:33]
	v_mfma_f32_16x16x32_bf16 v[10:13], v[86:89], v[222:225], v[10:13]
	v_mfma_f32_16x16x32_bf16 v[14:17], v[94:97], v[222:225], v[14:17]
	s_setprio 0
	s_barrier
	s_add_u32 s90, s20, 0x80000
	s_addc_u32 s91, s21, 0
	s_add_i32 s58, s59, s55
	s_mov_b32 m0, s58
	s_nop 0
	global_load_lds_dwordx4 v0, s[90:91]
	s_add_i32 m0, s58, 0x2000
	s_nop 0
	global_load_lds_dwordx4 v156, s[90:91]
	s_add_u32 s90, s20, s16
	s_addc_u32 s91, s21, s17
	s_waitcnt vmcnt(6)
	s_barrier
	s_setprio 1
	v_mfma_f32_16x16x32_bf16 v[50:53], v[226:229], v[166:169], v[50:53]
	v_mfma_f32_16x16x32_bf16 v[54:57], v[234:237], v[166:169], v[54:57]
	v_mfma_f32_16x16x32_bf16 v[34:37], v[226:229], v[176:179], v[34:37]
	v_mfma_f32_16x16x32_bf16 v[38:41], v[234:237], v[176:179], v[38:41]
	v_mfma_f32_16x16x32_bf16 v[18:21], v[226:229], v[210:213], v[18:21]
	v_mfma_f32_16x16x32_bf16 v[22:25], v[234:237], v[210:213], v[22:25]
	v_mfma_f32_16x16x32_bf16 v[6:9], v[226:229], v[218:221], v[6:9]
	v_mfma_f32_16x16x32_bf16 v[2:5], v[234:237], v[218:221], v[2:5]
	v_mfma_f32_16x16x32_bf16 v[50:53], v[230:233], v[172:175], v[50:53]
	v_mfma_f32_16x16x32_bf16 v[54:57], v[238:241], v[172:175], v[54:57]
	v_mfma_f32_16x16x32_bf16 v[34:37], v[230:233], v[206:209], v[34:37]
	v_mfma_f32_16x16x32_bf16 v[38:41], v[238:241], v[206:209], v[38:41]
	v_mfma_f32_16x16x32_bf16 v[18:21], v[230:233], v[214:217], v[18:21]
	v_mfma_f32_16x16x32_bf16 v[22:25], v[238:241], v[214:217], v[22:25]
	v_mfma_f32_16x16x32_bf16 v[6:9], v[230:233], v[222:225], v[6:9]
	v_mfma_f32_16x16x32_bf16 v[2:5], v[238:241], v[222:225], v[2:5]
	s_setprio 0
	s_add_i32 s58, 0, 0x18000
	s_barrier
	ds_read_b128 v[74:77], v150
	ds_read_b128 v[86:89], v150 offset:1024
	ds_read_b128 v[90:93], v150 offset:2048
	ds_read_b128 v[94:97], v150 offset:3072
	s_add_u32 s44, s44, 0x80000
	s_addc_u32 s45, s45, 0
	s_mov_b32 m0, s66
	ds_read_b128 v[166:169], v171 offset:32768
	ds_read_b128 v[172:175], v171 offset:33792
	ds_read_b128 v[176:179], v171 offset:34816
	ds_read_b128 v[206:209], v171 offset:35840
	ds_read_b128 v[210:213], v171 offset:36864
	ds_read_b128 v[214:217], v171 offset:37888
	ds_read_b128 v[218:221], v171 offset:38912
	global_load_lds_dwordx4 v160, s[44:45]
	s_mov_b32 m0, s67
	ds_read_b128 v[222:225], v171 offset:39936
	global_load_lds_dwordx4 v158, s[44:45]
	s_waitcnt lgkmcnt(8)
	s_barrier
; __device__ __forceinline__ int fresh_tid() { int t = threadIdx.x; asm volatile("" : "+v"(t)); return t; }
; #define PG8_STAGE(bufoff, gbase) PG8_STAGE_(bufoff, gbase, voffA)
; #define PG8_STAGEB(bufoff, gbase) PG8_STAGE_(bufoff, gbase, voffB)
; #define PG8_LDA(dst, b, h) do { _Pragma("unroll") for (int m = 0; m < 4; ++m) _Pragma("unroll") for (int k = 0; k < 2; ++k) dst[m][k] = *(const LAS bf16x8*)(lds + PG8_SA(b, h) + aoff + m * 2048 + k * 1024); } while (0)
; #define PG8_MMA(ai, bj, At, Bt) do { __builtin_amdgcn_s_setprio(1); _Pragma("unroll") for (int m = 0; m < 4; ++m) _Pragma("unroll") for (int n = 0; n < 2; ++n) _Pragma("unroll") for (int k = 0; k < 2; ++k) \
;         acc[ai][bj][m][n] = __builtin_amdgcn_mfma_f32_16x16x32_bf16(Bt[n][k], At[m][k], acc[ai][bj][m][n], 0, 0, 0); __builtin_amdgcn_s_setprio(0); } while (0)
; #define PG8_WAIT_V(n) asm volatile("s_waitcnt vmcnt(" #n ")" ::: "memory")
; #define PG8_WAIT_L(n) asm volatile("s_waitcnt lgkmcnt(" #n ")" ::: "memory")
; #define PG8_BAR __builtin_amdgcn_s_barrier()
; #define PG8_SCHED __builtin_amdgcn_sched_barrier(0)
; template <class Epi>
; __device__ __forceinline__ void gemm_phase(LAS unsigned char* lds, const Gemm g, const StaticOrder& S, const Epi& E) {
;     ...
;             PG8_BAR; PG8_WAIT_L(0); PG8_MMA(0, 1, At, B1); PG8_BAR;
;             PG8_LDA(At, 1, 1); PG8_STAGE(PG8_SA(1, 0), a3);
;             PG8_BAR; PG8_WAIT_L(0); PG8_MMA(1, 0, At, B0); PG8_BAR; PG8_SCHED;
;             PG8_STAGEB(PG8_SB(1, 1), b3 + hstep);
;             PG8_WAIT_V(6); PG8_BAR; PG8_MMA(1, 1, At, B1); PG8_BAR;
;         }
;         { const int t2 = fresh_tid(); const int w2 = __builtin_amdgcn_readfirstlane(t2 >> 6); E(acc, cur, w2 >> 2, w2 & 3, t2 & 15, (t2 >> 4) & 3); }
;     __device__ __forceinline__ void operator()(AccT& acc, const Unit& u, int wr, int wc, int fr, int fq) const {
;         int row0 = u.pm * 256 + wr * 64 + fr, col0 = u.pn * 256 + wc * 32 + 8 * fq;
;         asm volatile("" : "+v"(row0), "+v"(col0));
;         const bool gate = u.pn >= 37;
;         f32x4 bv[2][2];
; #pragma unroll
;         for (int bj = 0; bj < 2; ++bj)
; #pragma unroll
;             for (int n = 0; n < 2; ++n) bv[bj][n] = gate ? *(const f32x4*)(mb + (col0 - GATE0) + bj * 128 + n * 4) : (f32x4){0.f, 0.f, 0.f, 0.f};
	s_waitcnt lgkmcnt(0)
	s_setprio 1
	s_waitcnt lgkmcnt(0)
	v_mfma_f32_16x16x32_bf16 v[138:141], v[74:77], v[166:169], v[138:141]
	v_mfma_f32_16x16x32_bf16 v[142:145], v[90:93], v[166:169], v[142:145]
	v_mfma_f32_16x16x32_bf16 v[122:125], v[74:77], v[176:179], v[122:125]
	v_mfma_f32_16x16x32_bf16 v[126:129], v[90:93], v[176:179], v[126:129]
	v_mfma_f32_16x16x32_bf16 v[106:109], v[74:77], v[210:213], v[106:109]
	v_mfma_f32_16x16x32_bf16 v[110:113], v[90:93], v[210:213], v[110:113]
	v_mfma_f32_16x16x32_bf16 v[78:81], v[74:77], v[218:221], v[78:81]
	v_mfma_f32_16x16x32_bf16 v[82:85], v[90:93], v[218:221], v[82:85]
	v_mfma_f32_16x16x32_bf16 v[138:141], v[86:89], v[172:175], v[138:141]
	v_mfma_f32_16x16x32_bf16 v[142:145], v[94:97], v[172:175], v[142:145]
	v_mfma_f32_16x16x32_bf16 v[122:125], v[86:89], v[206:209], v[122:125]
	v_mfma_f32_16x16x32_bf16 v[126:129], v[94:97], v[206:209], v[126:129]
	v_mfma_f32_16x16x32_bf16 v[106:109], v[86:89], v[214:217], v[106:109]
	v_mfma_f32_16x16x32_bf16 v[110:113], v[94:97], v[214:217], v[110:113]
	v_mfma_f32_16x16x32_bf16 v[78:81], v[86:89], v[222:225], v[78:81]
	v_mfma_f32_16x16x32_bf16 v[82:85], v[94:97], v[222:225], v[82:85]
	s_setprio 0
	s_barrier
	s_add_i32 s44, 0, 0x1c000
	s_add_i32 s45, s58, s55
	s_mov_b32 m0, s45
	ds_read_b128 v[226:229], v151
	ds_read_b128 v[230:233], v151 offset:1024
	ds_read_b128 v[234:237], v151 offset:2048
	global_load_lds_dwordx4 v0, s[90:91]
	s_add_i32 m0, s45, 0x2000
	ds_read_b128 v[238:241], v151 offset:3072
	global_load_lds_dwordx4 v156, s[90:91]
	s_barrier
	s_waitcnt lgkmcnt(0)
	s_setprio 1
	s_waitcnt lgkmcnt(0)
	v_mfma_f32_16x16x32_bf16 v[130:133], v[226:229], v[166:169], v[130:133]
	v_mfma_f32_16x16x32_bf16 v[134:137], v[234:237], v[166:169], v[134:137]
	v_mfma_f32_16x16x32_bf16 v[114:117], v[226:229], v[176:179], v[114:117]
	v_mfma_f32_16x16x32_bf16 v[118:121], v[234:237], v[176:179], v[118:121]
	v_mfma_f32_16x16x32_bf16 v[98:101], v[226:229], v[210:213], v[98:101]
	v_mfma_f32_16x16x32_bf16 v[102:105], v[234:237], v[210:213], v[102:105]
	v_mfma_f32_16x16x32_bf16 v[66:69], v[226:229], v[218:221], v[66:69]
	v_mfma_f32_16x16x32_bf16 v[70:73], v[234:237], v[218:221], v[70:73]
	v_mfma_f32_16x16x32_bf16 v[130:133], v[230:233], v[172:175], v[130:133]
	v_mfma_f32_16x16x32_bf16 v[134:137], v[238:241], v[172:175], v[134:137]
	v_mfma_f32_16x16x32_bf16 v[114:117], v[230:233], v[206:209], v[114:117]
	v_mfma_f32_16x16x32_bf16 v[118:121], v[238:241], v[206:209], v[118:121]
	v_mfma_f32_16x16x32_bf16 v[98:101], v[230:233], v[214:217], v[98:101]
	v_mfma_f32_16x16x32_bf16 v[102:105], v[238:241], v[214:217], v[102:105]
	v_mfma_f32_16x16x32_bf16 v[66:69], v[230:233], v[222:225], v[66:69]
	v_mfma_f32_16x16x32_bf16 v[70:73], v[238:241], v[222:225], v[70:73]
	s_setprio 0
	s_mov_b32 m0, s38
	s_barrier
	ds_read_b128 v[166:169], v171 offset:49152
	ds_read_b128 v[172:175], v171 offset:50176
	ds_read_b128 v[176:179], v171 offset:51200
	ds_read_b128 v[206:209], v171 offset:52224
	ds_read_b128 v[210:213], v171 offset:53248
	ds_read_b128 v[214:217], v171 offset:54272
	ds_read_b128 v[218:221], v171 offset:55296
	global_load_lds_dwordx4 v160, s[100:101]
	s_mov_b32 m0, s80
	ds_read_b128 v[222:225], v171 offset:56320
	global_load_lds_dwordx4 v158, s[100:101]
	s_barrier
	s_waitcnt lgkmcnt(0)
	s_setprio 1
	s_waitcnt lgkmcnt(0)
	v_mfma_f32_16x16x32_bf16 v[58:61], v[74:77], v[166:169], v[58:61]
	v_mfma_f32_16x16x32_bf16 v[62:65], v[90:93], v[166:169], v[62:65]
	v_mfma_f32_16x16x32_bf16 v[42:45], v[74:77], v[176:179], v[42:45]
	v_mfma_f32_16x16x32_bf16 v[46:49], v[90:93], v[176:179], v[46:49]
	v_mfma_f32_16x16x32_bf16 v[26:29], v[74:77], v[210:213], v[26:29]
	v_mfma_f32_16x16x32_bf16 v[30:33], v[90:93], v[210:213], v[30:33]
	v_mfma_f32_16x16x32_bf16 v[10:13], v[74:77], v[218:221], v[10:13]
	v_mfma_f32_16x16x32_bf16 v[14:17], v[90:93], v[218:221], v[14:17]
	v_mfma_f32_16x16x32_bf16 v[58:61], v[86:89], v[172:175], v[58:61]
	v_mfma_f32_16x16x32_bf16 v[62:65], v[94:97], v[172:175], v[62:65]
	v_mfma_f32_16x16x32_bf16 v[42:45], v[86:89], v[206:209], v[42:45]
	v_mfma_f32_16x16x32_bf16 v[46:49], v[94:97], v[206:209], v[46:49]
	v_mfma_f32_16x16x32_bf16 v[26:29], v[86:89], v[214:217], v[26:29]
	v_mfma_f32_16x16x32_bf16 v[30:33], v[94:97], v[214:217], v[30:33]
	v_mfma_f32_16x16x32_bf16 v[10:13], v[86:89], v[222:225], v[10:13]
	v_mfma_f32_16x16x32_bf16 v[14:17], v[94:97], v[222:225], v[14:17]
	s_setprio 0
	s_barrier
	s_add_u32 s20, s20, 0x80080
	s_addc_u32 s21, s21, 0
	s_add_i32 s44, s44, s55
	s_mov_b32 m0, s44
	s_nop 0
	global_load_lds_dwordx4 v0, s[20:21]
	s_add_i32 m0, s44, 0x2000
	s_nop 0
	global_load_lds_dwordx4 v156, s[20:21]
	s_waitcnt vmcnt(6)
	s_barrier
	s_setprio 1
	v_mfma_f32_16x16x32_bf16 v[50:53], v[226:229], v[166:169], v[50:53]
	v_mfma_f32_16x16x32_bf16 v[54:57], v[234:237], v[166:169], v[54:57]
	v_mfma_f32_16x16x32_bf16 v[34:37], v[226:229], v[176:179], v[34:37]
	v_mfma_f32_16x16x32_bf16 v[38:41], v[234:237], v[176:179], v[38:41]
	v_mfma_f32_16x16x32_bf16 v[18:21], v[226:229], v[210:213], v[18:21]
	v_mfma_f32_16x16x32_bf16 v[22:25], v[234:237], v[210:213], v[22:25]
	v_mfma_f32_16x16x32_bf16 v[6:9], v[226:229], v[218:221], v[6:9]
	v_mfma_f32_16x16x32_bf16 v[2:5], v[234:237], v[218:221], v[2:5]
	v_mfma_f32_16x16x32_bf16 v[50:53], v[230:233], v[172:175], v[50:53]
	v_mfma_f32_16x16x32_bf16 v[54:57], v[238:241], v[172:175], v[54:57]
	v_mfma_f32_16x16x32_bf16 v[34:37], v[230:233], v[206:209], v[34:37]
	v_mfma_f32_16x16x32_bf16 v[38:41], v[238:241], v[206:209], v[38:41]
	v_mfma_f32_16x16x32_bf16 v[18:21], v[230:233], v[214:217], v[18:21]
	v_mfma_f32_16x16x32_bf16 v[22:25], v[238:241], v[214:217], v[22:25]
	v_mfma_f32_16x16x32_bf16 v[6:9], v[230:233], v[222:225], v[6:9]
	v_mfma_f32_16x16x32_bf16 v[2:5], v[238:241], v[222:225], v[2:5]
	s_setprio 0
	s_add_i32 s88, s88, 2
	s_add_u32 s30, s30, 0x100
	s_addc_u32 s31, s31, 0
	s_add_u32 s86, s86, 0x100
	s_addc_u32 s87, s87, 0
	s_cmp_gt_u32 s88, 29
	s_barrier
	s_cbranch_scc0 .LBB0_426
	v_mov_b32_e32 v74, v250
	s_lshl_b32 s21, s83, 8
	v_readfirstlane_b32 s20, v74
	s_ashr_i32 s25, s20, 2
	s_andn2_b32 s25, s25, 63
	s_lshr_b32 s20, s20, 1
	s_add_i32 s25, s25, s21
	s_lshl_b32 s21, s82, 8
	s_and_b32 s20, s20, 0x60
	v_and_or_b32 v172, v74, 15, s25
	s_or_b32 s20, s20, s21
	v_lshrrev_b32_e32 v74, 1, v74
	v_and_or_b32 v166, v74, 24, s20
	s_cmp_gt_i32 s82, 36
	v_ashrrev_i32_e32 v167, 31, v166
	v_mov_b32_e32 v90, 0
	s_cselect_b64 s[20:21], -1, 0
	s_cmp_lt_i32 s82, 37
	v_lshl_add_u64 v[168:169], v[166:167], 2, s[6:7]
	v_mov_b32_e32 v94, 0
	v_mov_b32_e32 v95, v90
	v_mov_b32_e32 v96, 0
	v_mov_b32_e32 v97, 0
	s_cbranch_scc1 .LBB0_429
	v_add_co_u32_e32 v74, vcc, 0xffff7000, v168
	s_nop 1
	v_addc_co_u32_e32 v75, vcc, -1, v169, vcc
	global_load_dwordx4 v[94:97], v[74:75], off offset:-1024
